# P1: column-tile order rotated so the late-read gate tiles are computed first and the tiles P2 reads are written last (on top of nt gate stores)
# baseline (speedup 1.0000x reference)
; #define PG8_STAGE(bufoff, gbase, voff) do { _Pragma("unroll") for (int _i = 0; _i < 2; ++_i) \
;         __builtin_amdgcn_global_load_lds((const unsigned*)((const char*)(gbase) + (voff)[_i]), (LAS unsigned*)(lds + (bufoff) + ldsw + _i * 8192), 16, 0, 0); } while (0)
;     __device__ bool next(int i, Unit& u) const {
;         const long L = (long)i * G + c; if (L >= nwg) return false;
;         int wgid = (int)L; { const int q = nwg / NXCD, r = nwg % NXCD, xcd = wgid % NXCD, off = wgid / NXCD; wgid = (xcd < r ? xcd * (q + 1) : r * (q + 1) + (xcd - r) * q) + off; }
;         const int nig = WGM * nN, gid = wgid / nig, fm = gid * WGM, gsz = (nM - fm) < WGM ? (nM - fm) : WGM;
;         u.pm = fm + ((wgid % nig) % gsz); u.pn = (wgid % nig) / gsz; return true;
; template <class Epi>
; __device__ __forceinline__ void gemm_phase(LAS unsigned char* lds, const Gemm g, const StaticOrder& S, const Epi& E) {
;     ...
;     const char* cA = (const char*)g.A + (size_t)cur.pm * tstep; const char* cB = (const char*)g.Bt + (size_t)cur.pn * tstep;
;     PG8_STAGE(PG8_SB(0, 0), cB, voffB); PG8_STAGE(PG8_SB(0, 1), cB + hstep, voffB); PG8_STAGE(PG8_SA(0, 0), cA, voffA); PG8_STAGE(PG8_SA(0, 1), cA + hstep, voffA);
.LBB0_116:
	v_readlane_b32 s0, v251, 3
	v_readlane_b32 s4, v250, 5
	v_readlane_b32 s1, v251, 4
	s_cmp_ge_i32 s4, s0
	s_cselect_b64 s[8:9], -1, 0
	s_cmp_lt_i32 s4, s1
	s_cselect_b64 s[0:1], -1, 0
	s_and_b64 s[0:1], s[8:9], s[0:1]
	s_andn2_b64 vcc, exec, s[0:1]
	s_cbranch_vccnz .LBB0_151
	v_readlane_b32 s12, v251, 5
	v_readlane_b32 s14, v251, 7
	v_readlane_b32 s15, v251, 8
	s_mov_b64 s[0:1], s[14:15]
	v_readlane_b32 s63, v251, 0
	s_mov_b32 s72, 2
	s_cmp_lt_i32 s72, 1
	v_readlane_b32 s13, v251, 6
	s_cbranch_scc1 .LBB0_151
	v_readlane_b32 s4, v250, 37
	v_readlane_b32 s5, v250, 38
	s_mul_i32 s30, s4, 0x740000
	s_add_u32 s10, s0, 0xdc00000
	s_addc_u32 s11, s1, 0
	s_lshl_b64 s[4:5], s[30:31], 1
	s_add_u32 s12, s0, s4
	s_addc_u32 s13, s1, s5
	s_add_u32 s14, s0, 0xfc80000
	s_addc_u32 s15, s1, 0
	s_add_u32 s22, s0, 0x2dfb4000
	s_addc_u32 s23, s1, 0
	s_bitcmp1_b32 s63, 0
	s_cselect_b64 s[0:1], -1, 0
	s_cmpk_lt_i32 s63, 0x700
	s_cselect_b64 s[28:29], -1, 0
	s_ashr_i32 s30, s63, 31
	s_lshr_b32 s4, s30, 29
	s_add_i32 s4, s63, s4
	s_ashr_i32 s5, s4, 3
	s_and_b32 s4, s4, -8
	s_sub_i32 s4, s63, s4
	s_cmp_lt_i32 s4, 0
	s_movk_i32 s34, 0xe1
	s_cselect_b32 s34, s34, 0xe0
	s_mul_i32 s4, s4, s34
	s_add_i32 s4, s4, s5
	s_mul_hi_i32 s5, s4, 0x92492493
	s_add_i32 s5, s5, s4
	s_lshr_b32 s34, s5, 31
	s_ashr_i32 s5, s5, 7
	s_add_i32 s5, s5, s34
	s_lshl_b32 s34, s5, 3
	s_mulk_i32 s5, 0xe0
	s_sub_i32 s5, s4, s5
	s_bfe_u32 s4, s5, 0x3001c
	s_add_i32 s35, s5, s4
	s_sext_i32_i16 s38, s35
	s_and_b32 s35, s35, 0xfff8
	s_sub_i32 s5, s5, s35
	s_sext_i32_i16 s5, s5
	s_addk_i32 s38, 0x80
	s_cmpk_ge_i32 s38, 0xe0
	s_cselect_b32 s35, 0xe0, 0
	s_sub_i32 s38, s38, s35
	s_lshr_b32 s4, s38, 3
	s_add_i32 s34, s34, s5
	s_ashr_i32 s35, s34, 31
	s_bfe_i64 s[4:5], s[4:5], 0x100000
	s_ashr_i32 s74, s38, 3
	s_lshl_b64 s[38:39], s[34:35], 19
	s_lshl_b64 s[4:5], s[4:5], 19
	s_add_u32 s42, s12, s4
	s_addc_u32 s43, s13, s5
	s_add_u32 s44, s42, 0x40000
	s_addc_u32 s45, s43, 0
	s_add_u32 s46, s10, s38
	s_addc_u32 s47, s11, s39
	s_add_u32 s48, s46, 0x40000
	s_addc_u32 s49, s47, 0
	s_add_u32 s50, s42, 0x40080
	s_mov_b32 s73, 0
	s_addc_u32 s51, s43, 0
	v_cndmask_b32_e64 v158, 0, 1, s[0:1]
	s_branch .LBB0_120

; template <class Epi>
; __device__ __forceinline__ void gemm_phase(LAS unsigned char* lds, const Gemm g, const StaticOrder& S, const Epi& E) {
;     ...
;         const bool has_next = S.next(ui + 1, nxt);
;         const char* nA = has_next ? (const char*)g.A + (size_t)nxt.pm * tstep : cA; const char* nB = has_next ? (const char*)g.Bt + (size_t)nxt.pn * tstep : cB;
;     ...
; #pragma unroll
;         for (int a = 0; a < 2; ++a)
; #pragma unroll
;             for (int b = 0; b < 2; ++b)
; #pragma unroll
;                 for (int m = 0; m < 4; ++m)
; #pragma unroll
;                     for (int n = 0; n < 2; ++n) acc[a][b][m][n] = (f32x4){0.f, 0.f, 0.f, 0.f};
.LBB0_129:
	s_add_i32 s52, s52, 16
	s_cmp_ge_i32 s52, 28
	s_cselect_b32 s53, 28, 0
	s_sub_i32 s52, s52, s53
	s_ashr_i32 s55, s54, 31
	s_lshl_b64 s[56:57], s[54:55], 19
	s_add_u32 s56, s10, s56
	s_addc_u32 s57, s11, s57
	s_and_b64 s[60:61], s[38:39], exec
	s_cselect_b32 s55, s57, s5
	s_cselect_b32 s84, s56, s4
	s_ashr_i32 s53, s52, 31
	s_lshl_b64 s[60:61], s[52:53], 19
	s_add_u32 s60, s12, s60
	s_addc_u32 s61, s13, s61
	s_and_b64 s[70:71], s[38:39], exec
	s_cselect_b32 s53, s61, s69
	s_cselect_b32 s85, s60, s68
	s_add_u32 s86, s68, 0x100
	s_addc_u32 s87, s69, 0
	s_add_u32 s4, s4, 0x40080
	v_mov_b32_e32 v2, 0
	s_addc_u32 s5, s5, 0
	s_mov_b32 s88, -2
	v_mov_b32_e32 v3, v2
	v_mov_b32_e32 v4, v2
	v_mov_b32_e32 v5, v2
	v_mov_b32_e32 v6, v2
	v_mov_b32_e32 v7, v2
	v_mov_b32_e32 v8, v2
	v_mov_b32_e32 v9, v2
	v_mov_b32_e32 v18, v2
	v_mov_b32_e32 v19, v2
	v_mov_b32_e32 v20, v2
	v_mov_b32_e32 v21, v2
	v_mov_b32_e32 v22, v2
	v_mov_b32_e32 v23, v2
	v_mov_b32_e32 v24, v2
	v_mov_b32_e32 v25, v2
	v_mov_b32_e32 v34, v2
	v_mov_b32_e32 v35, v2
	v_mov_b32_e32 v36, v2
	v_mov_b32_e32 v37, v2
	v_mov_b32_e32 v38, v2
	v_mov_b32_e32 v39, v2
	v_mov_b32_e32 v40, v2
	v_mov_b32_e32 v41, v2
	v_mov_b32_e32 v50, v2
	v_mov_b32_e32 v51, v2
	v_mov_b32_e32 v52, v2
	v_mov_b32_e32 v53, v2
	v_mov_b32_e32 v54, v2
	v_mov_b32_e32 v55, v2
	v_mov_b32_e32 v56, v2
	v_mov_b32_e32 v57, v2
	v_mov_b32_e32 v10, v2
	v_mov_b32_e32 v11, v2
	v_mov_b32_e32 v12, v2
	v_mov_b32_e32 v13, v2
	v_mov_b32_e32 v14, v2
	v_mov_b32_e32 v15, v2
	v_mov_b32_e32 v16, v2
	v_mov_b32_e32 v17, v2
	v_mov_b32_e32 v26, v2
	v_mov_b32_e32 v27, v2
	v_mov_b32_e32 v28, v2
	v_mov_b32_e32 v29, v2
	v_mov_b32_e32 v30, v2
	v_mov_b32_e32 v31, v2
	v_mov_b32_e32 v32, v2
	v_mov_b32_e32 v33, v2
	v_mov_b32_e32 v42, v2
	v_mov_b32_e32 v43, v2
	v_mov_b32_e32 v44, v2
	v_mov_b32_e32 v45, v2
	v_mov_b32_e32 v46, v2
	v_mov_b32_e32 v47, v2
	v_mov_b32_e32 v48, v2
	v_mov_b32_e32 v49, v2
	v_mov_b32_e32 v58, v2
	v_mov_b32_e32 v59, v2
	v_mov_b32_e32 v60, v2
	v_mov_b32_e32 v61, v2
	v_mov_b32_e32 v62, v2
	v_mov_b32_e32 v63, v2
	v_mov_b32_e32 v64, v2
	v_mov_b32_e32 v65, v2
	v_mov_b32_e32 v66, v2
	v_mov_b32_e32 v67, v2
	v_mov_b32_e32 v68, v2
	v_mov_b32_e32 v69, v2
	v_mov_b32_e32 v70, v2
	v_mov_b32_e32 v71, v2
	v_mov_b32_e32 v72, v2
	v_mov_b32_e32 v73, v2
	v_mov_b32_e32 v82, v2
	v_mov_b32_e32 v83, v2
	v_mov_b32_e32 v84, v2
	v_mov_b32_e32 v85, v2
	v_mov_b32_e32 v86, v2
	v_mov_b32_e32 v87, v2
	v_mov_b32_e32 v88, v2
	v_mov_b32_e32 v89, v2
	v_mov_b32_e32 v98, v2
	v_mov_b32_e32 v99, v2
	v_mov_b32_e32 v100, v2
	v_mov_b32_e32 v101, v2
	v_mov_b32_e32 v102, v2
	v_mov_b32_e32 v103, v2
	v_mov_b32_e32 v104, v2
	v_mov_b32_e32 v105, v2
	v_mov_b32_e32 v114, v2
	v_mov_b32_e32 v115, v2
	v_mov_b32_e32 v116, v2
	v_mov_b32_e32 v117, v2
	v_mov_b32_e32 v118, v2
	v_mov_b32_e32 v119, v2
	v_mov_b32_e32 v120, v2
	v_mov_b32_e32 v121, v2
	v_mov_b32_e32 v74, v2
	v_mov_b32_e32 v75, v2
	v_mov_b32_e32 v76, v2
	v_mov_b32_e32 v77, v2
	v_mov_b32_e32 v78, v2
	v_mov_b32_e32 v79, v2
	v_mov_b32_e32 v80, v2
	v_mov_b32_e32 v81, v2
	v_mov_b32_e32 v90, v2
	v_mov_b32_e32 v91, v2
	v_mov_b32_e32 v92, v2
	v_mov_b32_e32 v93, v2
	v_mov_b32_e32 v94, v2
	v_mov_b32_e32 v95, v2
	v_mov_b32_e32 v96, v2
	v_mov_b32_e32 v97, v2
	v_mov_b32_e32 v106, v2
	v_mov_b32_e32 v107, v2
	v_mov_b32_e32 v108, v2
	v_mov_b32_e32 v109, v2
	v_mov_b32_e32 v110, v2
	v_mov_b32_e32 v111, v2
	v_mov_b32_e32 v112, v2
	v_mov_b32_e32 v113, v2
	v_mov_b32_e32 v122, v2
	v_mov_b32_e32 v123, v2
	v_mov_b32_e32 v124, v2
	v_mov_b32_e32 v125, v2
	v_mov_b32_e32 v126, v2
	v_mov_b32_e32 v127, v2
	v_mov_b32_e32 v128, v2
	v_mov_b32_e32 v129, v2
